# idx pass 1/2 score loops: two-trip-deep prefetch (2x unrolled register ring), scalar loop control, remainder K fragments fetched before the loop
# baseline (speedup 1.0000x reference)
; template <int PASS>
; DI void idx_pass(const u16* kp, const bf16x8 (&qf)[8], const float (&wq)[8], int wave, int ntile, int lm, int lg, int tq, bool selall,
;                  u32 bA, u32 pfx, u32* hist, u32* maskw, u32* cand, u32* ccnt) {
;   auto ldk = [&](int t) { return *(const bf16x8*)(kp + (size_t)(t < ntile ? t : 0) * 512); };
;   int kt = wave;
;   bf16x8 ka = ldk(kt), kb = ldk(kt + 4);
;   for (; kt + 4 < ntile - 1; kt += 8) {
;     const bf16x8 kc = ldk(kt + 8), kd = ldk(kt + 12);
;     idx_tile<PASS, false>(ka, qf, wq, kt, lm, lg, tq, selall, bA, pfx, hist, maskw, cand, ccnt);
;     idx_tile<PASS, false>(kb, qf, wq, kt + 4, lm, lg, tq, selall, bA, pfx, hist, maskw, cand, ccnt);
;     ka = kc; kb = kd;
;   }
.LBB0_602:
	s_or_b64 exec, exec, s[2:3]
	s_waitcnt lgkmcnt(0)
	s_barrier
	s_cbranch_vccz .Lidx1_nl
	v_sub_u32_e32 v160, v97, v109
	v_subrev_u32_e32 v160, 5, v160
	v_and_b32_e32 v160, -8, v160
	v_add_u32_e32 v160, v160, v109
	v_add_u32_e32 v162, 12, v160
	v_add_u32_e32 v160, 8, v160
	v_cmp_le_i32_e64 s[4:5], v160, v97
	v_cmp_le_i32_e64 s[8:9], v162, v97
	v_mov_b32_e32 v161, 0
	v_mov_b32_e32 v163, 0
	v_cndmask_b32_e64 v160, 0, v160, s[4:5]
	v_cndmask_b32_e64 v162, 0, v162, s[8:9]
	v_lshlrev_b64 v[160:161], 10, v[160:161]
	v_lshlrev_b64 v[162:163], 10, v[162:163]
	v_lshl_add_u64 v[160:161], v[90:91], 0, v[160:161]
	v_lshl_add_u64 v[162:163], v[90:91], 0, v[162:163]
	global_load_dwordx4 v[192:195], v[160:161], off
	global_load_dwordx4 v[226:229], v[162:163], off
	v_lshl_add_u32 v182, v109, 10, v250
	s_add_u32 s92, s90, 0x1000
	s_addc_u32 s93, s91, 0
	v_readfirstlane_b32 s88, v109
	v_readfirstlane_b32 s89, v97
	global_load_dwordx4 v[184:187], v182, s[90:91]
	global_load_dwordx4 v[188:191], v182, s[92:93]
	v_add_u32_e32 v183, 0x2000, v182
	global_load_dwordx4 v[230:233], v183, s[90:91]
	global_load_dwordx4 v[234:237], v183, s[92:93]
	v_add_u32_e32 v182, 0x4000, v182
	s_branch .Lidx1_pj
.Lidx1_nl:
	global_load_dwordx4 v[42:45], v[92:93], off
	global_load_dwordx4 v[46:49], v[94:95], off
.Lidx1_pj:
	v_lshl_add_u32 v136, v88, 2, v96
	ds_read_b32 v137, v136 offset:49472
	v_mov_b32_e32 v79, v0
	v_mov_b32_e32 v153, v109
	s_and_saveexec_b64 s[2:3], vcc
	s_cbranch_execz .LBB0_622
	v_lshl_add_u32 v154, v88, 11, v96
	s_waitcnt lgkmcnt(0)
.Lidx1_loop:
	s_waitcnt vmcnt(2)
	v_mov_b64_e32 v[82:83], v[184:185]
	v_mov_b64_e32 v[84:85], v[186:187]
	v_mov_b64_e32 v[46:47], v[188:189]
	v_mov_b64_e32 v[48:49], v[190:191]
	global_load_dwordx4 v[184:187], v182, s[90:91]
	global_load_dwordx4 v[188:191], v182, s[92:93]
	v_add_u32_e32 v182, 0x2000, v182
	v_ashrrev_i32_e32 v58, 31, v82
	v_bitop3_b32 v54, v58, v82, s39 bitop3:0x36
	v_lshrrev_b32_e32 v58, 22, v54
	v_cmp_eq_u32_e64 s[4:5], v58, v137
	s_and_saveexec_b64 s[8:9], s[4:5]
	s_cbranch_execz .Lidx1_skip0
	v_lshrrev_b32_e32 v58, 8, v54
	v_lshrrev_b32_e32 v54, 11, v54
	v_and_b32_e32 v58, 16, v58
	v_and_b32_e32 v54, 0x7fc, v54
	v_lshlrev_b32_e64 v58, v58, 1
	v_add_u32_e32 v54, v154, v54
	ds_add_u32 v54, v58

; template <int PASS, bool DIAG>
; DI void idx_tile(const bf16x8 kf, const bf16x8 (&qf)[8], const float (&wq)[8], int kt, int lm, int lg, int tq, bool selall, u32 bA, u32 pfx,
;                  u32* hist, u32* maskw, u32* cand, u32* ccnt) {
;     ...
;   for (int r = 0; r < 4; ++r) {
;     const int key = kt * 16 + lg * 4 + r;
;     const bool valid = !DIAG || key <= tq;
;     const u32 bits = __float_as_uint(sc[r]);
;     const u32 u = bits ^ ((u32)((int)bits >> 31) | 0x80000000u);
;     if (PASS == 0) {
;       if (valid) { const u32 bin = u >> 22; atomicAdd(&hist[lm * 512 + (bin >> 1)], 1u << ((bin & 1) * 16)); }
;     } else if (PASS == 1) {
;       if (valid && (u >> 22) == bA) { const u32 bin = (u >> 12) & 1023u; atomicAdd(&hist[lm * 512 + (bin >> 1)], 1u << ((bin & 1) * 16)); }
.Lidx1_skip3:
	s_or_b64 exec, exec, s[8:9]
	v_ashrrev_i32_e32 v58, 31, v46
	v_bitop3_b32 v54, v58, v46, s39 bitop3:0x36
	v_lshrrev_b32_e32 v58, 22, v54
	v_cmp_eq_u32_e64 s[4:5], v58, v137
	s_and_saveexec_b64 s[8:9], s[4:5]
	s_cbranch_execz .Lidx1_skip4
	v_lshrrev_b32_e32 v58, 8, v54
	v_lshrrev_b32_e32 v54, 11, v54
	v_and_b32_e32 v58, 16, v58
	v_and_b32_e32 v54, 0x7fc, v54
	v_lshlrev_b32_e64 v58, v58, 1
	v_add_u32_e32 v54, v154, v54
	ds_add_u32 v54, v58

; template <int PASS, bool DIAG>
; DI void idx_tile(const bf16x8 kf, const bf16x8 (&qf)[8], const float (&wq)[8], int kt, int lm, int lg, int tq, bool selall, u32 bA, u32 pfx,
;                  u32* hist, u32* maskw, u32* cand, u32* ccnt) {
;     ...
;   for (int r = 0; r < 4; ++r) {
;     const int key = kt * 16 + lg * 4 + r;
;     const bool valid = !DIAG || key <= tq;
;     const u32 bits = __float_as_uint(sc[r]);
;     const u32 u = bits ^ ((u32)((int)bits >> 31) | 0x80000000u);
;     if (PASS == 0) {
;       if (valid) { const u32 bin = u >> 22; atomicAdd(&hist[lm * 512 + (bin >> 1)], 1u << ((bin & 1) * 16)); }
;     } else if (PASS == 1) {
;       if (valid && (u >> 22) == bA) { const u32 bin = (u >> 12) & 1023u; atomicAdd(&hist[lm * 512 + (bin >> 1)], 1u << ((bin & 1) * 16)); }
; template <int PASS>
; DI void idx_pass(const u16* kp, const bf16x8 (&qf)[8], const float (&wq)[8], int wave, int ntile, int lm, int lg, int tq, bool selall,
;                  u32 bA, u32 pfx, u32* hist, u32* maskw, u32* cand, u32* ccnt) {
;     ...
;   for (; kt + 4 < ntile - 1; kt += 8) {
;     const bf16x8 kc = ldk(kt + 8), kd = ldk(kt + 12);
;     idx_tile<PASS, false>(ka, qf, wq, kt, lm, lg, tq, selall, bA, pfx, hist, maskw, cand, ccnt);
;     idx_tile<PASS, false>(kb, qf, wq, kt + 4, lm, lg, tq, selall, bA, pfx, hist, maskw, cand, ccnt);
;     ka = kc; kb = kd;
;   }
.Lidx1_skip7:
	s_or_b64 exec, exec, s[8:9]
	s_add_i32 s88, s88, 8
	s_add_i32 s4, s88, 4
	s_cmp_ge_i32 s4, s89
	s_cbranch_scc1 .Lidx1_done
	s_waitcnt vmcnt(2)
	v_mov_b64_e32 v[82:83], v[230:231]
	v_mov_b64_e32 v[84:85], v[232:233]
	v_mov_b64_e32 v[46:47], v[234:235]
	v_mov_b64_e32 v[48:49], v[236:237]
	global_load_dwordx4 v[230:233], v182, s[90:91]
	global_load_dwordx4 v[234:237], v182, s[92:93]
	v_add_u32_e32 v182, 0x2000, v182
	v_ashrrev_i32_e32 v58, 31, v82
	v_bitop3_b32 v54, v58, v82, s39 bitop3:0x36
	v_lshrrev_b32_e32 v58, 22, v54
	v_cmp_eq_u32_e64 s[4:5], v58, v137
	s_and_saveexec_b64 s[8:9], s[4:5]
	s_cbranch_execz .Lidx1_skip8
	v_lshrrev_b32_e32 v58, 8, v54
	v_lshrrev_b32_e32 v54, 11, v54
	v_and_b32_e32 v58, 16, v58
	v_and_b32_e32 v54, 0x7fc, v54
	v_lshlrev_b32_e64 v58, v58, 1
	v_add_u32_e32 v54, v154, v54
	ds_add_u32 v54, v58

; template <int PASS>
; DI void idx_pass(const u16* kp, const bf16x8 (&qf)[8], const float (&wq)[8], int wave, int ntile, int lm, int lg, int tq, bool selall,
;                  u32 bA, u32 pfx, u32* hist, u32* maskw, u32* cand, u32* ccnt) {
;     ...
;   for (; kt + 4 < ntile - 1; kt += 8) {
;     const bf16x8 kc = ldk(kt + 8), kd = ldk(kt + 12);
;     idx_tile<PASS, false>(ka, qf, wq, kt, lm, lg, tq, selall, bA, pfx, hist, maskw, cand, ccnt);
;     idx_tile<PASS, false>(kb, qf, wq, kt + 4, lm, lg, tq, selall, bA, pfx, hist, maskw, cand, ccnt);
;     ka = kc; kb = kd;
;   }
;   if (kt < ntile - 1) { idx_tile<PASS, false>(ka, qf, wq, kt, lm, lg, tq, selall, bA, pfx, hist, maskw, cand, ccnt); kt += 4; ka = kb; }
.Lidx1_skip15:
	s_or_b64 exec, exec, s[8:9]
	s_add_i32 s88, s88, 8
	s_add_i32 s4, s88, 4
	s_cmp_lt_i32 s4, s89
	s_cbranch_scc1 .Lidx1_loop
.Lidx1_done:
	s_waitcnt vmcnt(0)
	v_mov_b64_e32 v[42:43], v[192:193]
	v_mov_b64_e32 v[44:45], v[194:195]
	v_mov_b64_e32 v[46:47], v[226:227]
	v_mov_b64_e32 v[48:49], v[228:229]
	v_mov_b32_e32 v153, s88
	v_add_u32_e32 v79, 4, v153

; template <int PASS, bool DIAG>
; DI void idx_tile(const bf16x8 kf, const bf16x8 (&qf)[8], const float (&wq)[8], int kt, int lm, int lg, int tq, bool selall, u32 bA, u32 pfx,
;                  u32* hist, u32* maskw, u32* cand, u32* ccnt) {
;     ...
;   for (int r = 0; r < 4; ++r) {
;     const int key = kt * 16 + lg * 4 + r;
;     const bool valid = !DIAG || key <= tq;
;     const u32 bits = __float_as_uint(sc[r]);
;     const u32 u = bits ^ ((u32)((int)bits >> 31) | 0x80000000u);
;     if (PASS == 0) {
;       if (valid) { const u32 bin = u >> 22; atomicAdd(&hist[lm * 512 + (bin >> 1)], 1u << ((bin & 1) * 16)); }
;     } else if (PASS == 1) {
;       if (valid && (u >> 22) == bA) { const u32 bin = (u >> 12) & 1023u; atomicAdd(&hist[lm * 512 + (bin >> 1)], 1u << ((bin & 1) * 16)); }
;     } else {
;       const u32 pp = u >> 12;
;       if (valid && (selall || pp > pfx)) selbits |= 1u << r;
;       if (valid && !selall && pp == pfx) {
;         const u32 ix = atomicAdd(&ccnt[lm], 1u);
;         if (ix < 64u) { cand[(lm * 64 + ix) * 2] = u; cand[(lm * 64 + ix) * 2 + 1] = (u32)key; }
;       }
;     }
; template <int PASS>
; DI void idx_pass(const u16* kp, const bf16x8 (&qf)[8], const float (&wq)[8], int wave, int ntile, int lm, int lg, int tq, bool selall,
;                  u32 bA, u32 pfx, u32* hist, u32* maskw, u32* cand, u32* ccnt) {
;     ...
;   for (; kt + 4 < ntile - 1; kt += 8) {
;     const bf16x8 kc = ldk(kt + 8), kd = ldk(kt + 12);
;     idx_tile<PASS, false>(ka, qf, wq, kt, lm, lg, tq, selall, bA, pfx, hist, maskw, cand, ccnt);
;     idx_tile<PASS, false>(kb, qf, wq, kt + 4, lm, lg, tq, selall, bA, pfx, hist, maskw, cand, ccnt);
;     ka = kc; kb = kd;
; DI void idx_job(const Params& p, int b, int qg, unsigned char* smem) {
;     ...
;   idx_pass<2>(kp, qf, wq, wave, ntile, lm, lg, tq, selall, binA[lm], (binA[lm] << 10) | binB[lm], hist, maskw, cand, ccnt);
.Lidx2_pj:
	v_add_u32_e32 v50, 0xc000, v136
	ds_read2_b32 v[50:51], v50 offset0:80 offset1:112
	s_movk_i32 s2, 0x100
	v_cmp_gt_u32_e64 s[40:41], s2, v87
	s_waitcnt lgkmcnt(0)
	v_lshl_or_b32 v99, v50, 10, v51
	s_and_saveexec_b64 s[2:3], vcc
	s_xor_b64 s[2:3], exec, s[2:3]
	s_cbranch_execz .LBB0_863
	s_movk_i32 s4, 0x210
	v_lshl_add_u32 v100, v88, 9, v96
	v_mad_u32_u24 v101, v88, s4, v96
	v_lshl_add_u32 v102, v109, 4, 64
	s_mov_b64 s[4:5], 0
	s_xor_b64 s[6:7], s[40:41], -1
	v_add_u32_e32 v180, 1, v99
	v_cndmask_b32_e64 v180, v180, 0, s[40:41]
.Lidx2_loop:
	s_waitcnt vmcnt(2)
	v_mov_b64_e32 v[82:83], v[184:185]
	v_mov_b64_e32 v[84:85], v[186:187]
	v_mov_b64_e32 v[46:47], v[188:189]
	v_mov_b64_e32 v[48:49], v[190:191]
	global_load_dwordx4 v[184:187], v182, s[90:91]
	global_load_dwordx4 v[188:191], v182, s[92:93]
	v_add_u32_e32 v182, 0x2000, v182
	v_add_u32_e32 v93, v98, v102
	v_ashrrev_i32_e32 v181, 31, v82
	v_bitop3_b32 v168, v181, v82, s39 bitop3:0x36
	v_lshrrev_b32_e32 v176, 12, v168
	v_ashrrev_i32_e32 v181, 31, v83
	v_bitop3_b32 v170, v181, v83, s39 bitop3:0x36
	v_lshrrev_b32_e32 v177, 12, v170
	v_ashrrev_i32_e32 v181, 31, v84
	v_bitop3_b32 v172, v181, v84, s39 bitop3:0x36
	v_lshrrev_b32_e32 v178, 12, v172
	v_ashrrev_i32_e32 v181, 31, v85
	v_bitop3_b32 v174, v181, v85, s39 bitop3:0x36
	v_lshrrev_b32_e32 v179, 12, v174
	v_cmp_eq_u32_e64 s[8:9], v176, v99
	v_cmp_eq_u32_e64 s[28:29], v177, v99
	v_cmp_eq_u32_e64 s[94:95], v178, v99
	v_cmp_eq_u32_e32 vcc, v179, v99
	s_or_b64 s[8:9], s[8:9], s[28:29]
	s_or_b64 s[28:29], vcc, s[94:95]
	s_or_b64 s[8:9], s[8:9], s[28:29]
	s_and_b64 s[8:9], s[8:9], s[6:7]
	s_cbranch_scc0 .Lidx2_nc0
	v_cmp_eq_u32_e32 vcc, v176, v99
	s_and_b64 s[28:29], s[6:7], vcc
	s_and_saveexec_b64 s[8:9], s[28:29]
	s_cbranch_execz .Lidx2_c0_0
	ds_add_rtn_u32 v181, v136, v203 offset:49408
	s_waitcnt lgkmcnt(0)
	v_cmp_gt_u32_e32 vcc, 64, v181
	s_and_b64 exec, exec, vcc
	v_subrev_u32_e32 v169, 64, v93
	v_lshl_add_u32 v181, v181, 3, v100
	ds_write_b64 v181, v[168:169] offset:41216

; template <int PASS, bool DIAG>
; DI void idx_tile(const bf16x8 kf, const bf16x8 (&qf)[8], const float (&wq)[8], int kt, int lm, int lg, int tq, bool selall, u32 bA, u32 pfx,
;                  u32* hist, u32* maskw, u32* cand, u32* ccnt) {
;     ...
;   for (int r = 0; r < 4; ++r) {
;     const int key = kt * 16 + lg * 4 + r;
;     const bool valid = !DIAG || key <= tq;
;     const u32 bits = __float_as_uint(sc[r]);
;     const u32 u = bits ^ ((u32)((int)bits >> 31) | 0x80000000u);
;     if (PASS == 0) {
;       if (valid) { const u32 bin = u >> 22; atomicAdd(&hist[lm * 512 + (bin >> 1)], 1u << ((bin & 1) * 16)); }
;     } else if (PASS == 1) {
;       if (valid && (u >> 22) == bA) { const u32 bin = (u >> 12) & 1023u; atomicAdd(&hist[lm * 512 + (bin >> 1)], 1u << ((bin & 1) * 16)); }
;     } else {
;       const u32 pp = u >> 12;
;       if (valid && (selall || pp > pfx)) selbits |= 1u << r;
;       if (valid && !selall && pp == pfx) {
;         const u32 ix = atomicAdd(&ccnt[lm], 1u);
;         if (ix < 64u) { cand[(lm * 64 + ix) * 2] = u; cand[(lm * 64 + ix) * 2 + 1] = (u32)key; }
;       }
;     }
.Lidx2_o0:
	s_or_b64 exec, exec, s[8:9]
	v_ashrrev_i32_e32 v181, 31, v46
	v_bitop3_b32 v168, v181, v46, s39 bitop3:0x36
	v_lshrrev_b32_e32 v176, 12, v168
	v_ashrrev_i32_e32 v181, 31, v47
	v_bitop3_b32 v170, v181, v47, s39 bitop3:0x36
	v_lshrrev_b32_e32 v177, 12, v170
	v_ashrrev_i32_e32 v181, 31, v48
	v_bitop3_b32 v172, v181, v48, s39 bitop3:0x36
	v_lshrrev_b32_e32 v178, 12, v172
	v_ashrrev_i32_e32 v181, 31, v49
	v_bitop3_b32 v174, v181, v49, s39 bitop3:0x36
	v_lshrrev_b32_e32 v179, 12, v174
	v_cmp_eq_u32_e64 s[8:9], v176, v99
	v_cmp_eq_u32_e64 s[28:29], v177, v99
	v_cmp_eq_u32_e64 s[94:95], v178, v99
	v_cmp_eq_u32_e32 vcc, v179, v99
	s_or_b64 s[8:9], s[8:9], s[28:29]
	s_or_b64 s[28:29], vcc, s[94:95]
	s_or_b64 s[8:9], s[8:9], s[28:29]
	s_and_b64 s[8:9], s[8:9], s[6:7]
	s_cbranch_scc0 .Lidx2_nc1
	v_cmp_eq_u32_e32 vcc, v176, v99
	s_and_b64 s[28:29], s[6:7], vcc
	s_and_saveexec_b64 s[8:9], s[28:29]
	s_cbranch_execz .Lidx2_c1_0
	ds_add_rtn_u32 v181, v136, v203 offset:49408
	s_waitcnt lgkmcnt(0)
	v_cmp_gt_u32_e32 vcc, 64, v181
	s_and_b64 exec, exec, vcc
	v_mov_b32_e32 v169, v93
	v_lshl_add_u32 v181, v181, 3, v100
	ds_write_b64 v181, v[168:169] offset:41216

; template <int PASS, bool DIAG>
; DI void idx_tile(const bf16x8 kf, const bf16x8 (&qf)[8], const float (&wq)[8], int kt, int lm, int lg, int tq, bool selall, u32 bA, u32 pfx,
;                  u32* hist, u32* maskw, u32* cand, u32* ccnt) {
;     ...
;       const u32 pp = u >> 12;
;       if (valid && (selall || pp > pfx)) selbits |= 1u << r;
;       if (valid && !selall && pp == pfx) {
;         const u32 ix = atomicAdd(&ccnt[lm], 1u);
;         if (ix < 64u) { cand[(lm * 64 + ix) * 2] = u; cand[(lm * 64 + ix) * 2 + 1] = (u32)key; }
;       }
;     }
;   }
;   if (PASS == 2 && selbits) {
;     const int kb = kt * 16 + lg * 4;
;     atomicOr(&maskw[lm * MW + (kb >> 5)], selbits << (kb & 31));
;   }
; template <int PASS>
; DI void idx_pass(const u16* kp, const bf16x8 (&qf)[8], const float (&wq)[8], int wave, int ntile, int lm, int lg, int tq, bool selall,
;                  u32 bA, u32 pfx, u32* hist, u32* maskw, u32* cand, u32* ccnt) {
;     ...
;   for (; kt + 4 < ntile - 1; kt += 8) {
;     const bf16x8 kc = ldk(kt + 8), kd = ldk(kt + 12);
;     idx_tile<PASS, false>(ka, qf, wq, kt, lm, lg, tq, selall, bA, pfx, hist, maskw, cand, ccnt);
;     idx_tile<PASS, false>(kb, qf, wq, kt + 4, lm, lg, tq, selall, bA, pfx, hist, maskw, cand, ccnt);
;     ka = kc; kb = kd;
;   }
.Lidx2_nc1:
	v_cmp_ge_u32_e64 s[8:9], v176, v180
	v_cmp_ge_u32_e64 s[28:29], v177, v180
	v_cmp_ge_u32_e64 s[94:95], v178, v180
	v_cmp_ge_u32_e32 vcc, v179, v180
	v_cndmask_b32_e64 v0, 0, 1, s[8:9]
	v_cndmask_b32_e64 v54, 0, 2, s[28:29]
	v_cndmask_b32_e64 v55, 0, 4, s[94:95]
	v_cndmask_b32_e64 v56, 0, 8, vcc
	v_or_b32_e32 v0, v54, v0
	v_or3_b32 v0, v0, v55, v56
	v_cmp_ne_u32_e32 vcc, 0, v0
	s_and_saveexec_b64 s[8:9], vcc
	s_cbranch_execz .Lidx2_o1
	v_lshl_add_u32 v54, v109, 1, 8
	v_and_b32_e32 v54, -4, v54
	v_and_or_b32 v55, v102, 16, v98
	v_add_u32_e32 v54, v101, v54
	v_lshlrev_b32_e32 v0, v55, v0
	ds_or_b32 v54, v0 offset:32768
.Lidx2_o1:
	s_or_b64 exec, exec, s[8:9]
	v_add_u32_e32 v102, 0x80, v102
	v_add_u32_e32 v109, 8, v109
	s_add_i32 s88, s88, 8
	s_add_i32 s4, s88, 4
	s_cmp_ge_i32 s4, s89
	s_cbranch_scc1 .Lidx2_done
	s_waitcnt vmcnt(2)
	v_mov_b64_e32 v[82:83], v[230:231]
	v_mov_b64_e32 v[84:85], v[232:233]
	v_mov_b64_e32 v[46:47], v[234:235]
	v_mov_b64_e32 v[48:49], v[236:237]
	global_load_dwordx4 v[230:233], v182, s[90:91]
	global_load_dwordx4 v[234:237], v182, s[92:93]
	v_add_u32_e32 v182, 0x2000, v182
	v_add_u32_e32 v93, v98, v102
	v_ashrrev_i32_e32 v181, 31, v82
	v_bitop3_b32 v168, v181, v82, s39 bitop3:0x36
	v_lshrrev_b32_e32 v176, 12, v168
	v_ashrrev_i32_e32 v181, 31, v83
	v_bitop3_b32 v170, v181, v83, s39 bitop3:0x36
	v_lshrrev_b32_e32 v177, 12, v170
	v_ashrrev_i32_e32 v181, 31, v84
	v_bitop3_b32 v172, v181, v84, s39 bitop3:0x36
	v_lshrrev_b32_e32 v178, 12, v172
	v_ashrrev_i32_e32 v181, 31, v85
	v_bitop3_b32 v174, v181, v85, s39 bitop3:0x36
	v_lshrrev_b32_e32 v179, 12, v174
	v_cmp_eq_u32_e64 s[8:9], v176, v99
	v_cmp_eq_u32_e64 s[28:29], v177, v99
	v_cmp_eq_u32_e64 s[94:95], v178, v99
	v_cmp_eq_u32_e32 vcc, v179, v99
	s_or_b64 s[8:9], s[8:9], s[28:29]
	s_or_b64 s[28:29], vcc, s[94:95]
	s_or_b64 s[8:9], s[8:9], s[28:29]
	s_and_b64 s[8:9], s[8:9], s[6:7]
	s_cbranch_scc0 .Lidx2_nc2
	v_cmp_eq_u32_e32 vcc, v176, v99
	s_and_b64 s[28:29], s[6:7], vcc
	s_and_saveexec_b64 s[8:9], s[28:29]
	s_cbranch_execz .Lidx2_c2_0
	ds_add_rtn_u32 v181, v136, v203 offset:49408
	s_waitcnt lgkmcnt(0)
	v_cmp_gt_u32_e32 vcc, 64, v181
	s_and_b64 exec, exec, vcc
	v_subrev_u32_e32 v169, 64, v93
	v_lshl_add_u32 v181, v181, 3, v100
	ds_write_b64 v181, v[168:169] offset:41216

; template <int PASS>
; DI void idx_pass(const u16* kp, const bf16x8 (&qf)[8], const float (&wq)[8], int wave, int ntile, int lm, int lg, int tq, bool selall,
;                  u32 bA, u32 pfx, u32* hist, u32* maskw, u32* cand, u32* ccnt) {
;     ...
;   for (; kt + 4 < ntile - 1; kt += 8) {
;     const bf16x8 kc = ldk(kt + 8), kd = ldk(kt + 12);
;     idx_tile<PASS, false>(ka, qf, wq, kt, lm, lg, tq, selall, bA, pfx, hist, maskw, cand, ccnt);
;     idx_tile<PASS, false>(kb, qf, wq, kt + 4, lm, lg, tq, selall, bA, pfx, hist, maskw, cand, ccnt);
;     ka = kc; kb = kd;
;   }
;   if (kt < ntile - 1) { idx_tile<PASS, false>(ka, qf, wq, kt, lm, lg, tq, selall, bA, pfx, hist, maskw, cand, ccnt); kt += 4; ka = kb; }
;   if (kt == ntile - 1) idx_tile<PASS, true>(ka, qf, wq, kt, lm, lg, tq, selall, bA, pfx, hist, maskw, cand, ccnt);
.Lidx2_o3:
	s_or_b64 exec, exec, s[8:9]
	v_add_u32_e32 v102, 0x80, v102
	v_add_u32_e32 v109, 8, v109
	s_add_i32 s88, s88, 8
	s_add_i32 s4, s88, 4
	s_cmp_lt_i32 s4, s89
	s_cbranch_scc1 .Lidx2_loop
.Lidx2_done:
	s_waitcnt vmcnt(0)
	v_mov_b64_e32 v[42:43], v[192:193]
	v_mov_b64_e32 v[44:45], v[194:195]
	v_mov_b64_e32 v[46:47], v[226:227]
	v_mov_b64_e32 v[48:49], v[228:229]
	v_add_u32_e32 v0, 4, v109
	v_mov_b32_e32 v103, v109
